# v7: + P4 rs loads hoisted, P10 epilogue conv-weight loads issued before the row-exchange barrier
# speedup vs baseline: 1.0025x; 1.0025x over previous
; #define PG8_LAS __attribute__((address_space(3)))
;     __device__ __forceinline__ void operator()(const f32x4 (&acc)[2][2][4][2], const Unit& u, int wr, int wc, int fr, int fq) const {
;     ...
;         if (fr == 0) {
; #pragma unroll
;             for (int ai = 0; ai < 2; ++ai)
; #pragma unroll
;                 for (int bj = 0; bj < 2; ++bj)
; #pragma unroll
;                     for (int n = 0; n < 2; ++n) *(PG8_LAS f32x4*)(EX + ((2 * ai + wr) * 2 + 0) * 256 + 128 * bj + cl0 + 4 * n) = acc[ai][bj][0][n];
;         }
;     ...
;             const int ch = u.pn * 128 + cl0 + 4 * n;
;             const f32x4 w0a = *(const f32x4*)(cw + ch), w1a = *(const f32x4*)(cw + 11264 + ch), w2a = *(const f32x4*)(cw + 2 * 11264 + ch);
;             const f32x4 w0b = *(const f32x4*)(cw + 5632 + ch), w1b = *(const f32x4*)(cw + 11264 + 5632 + ch), w2b = *(const f32x4*)(cw + 2 * 11264 + 5632 + ch);
;             const f32x4 ba = *(const f32x4*)(cb + ch), bb = *(const f32x4*)(cb + 5632 + ch);
.LBB0_931:
	s_lshl_b32 s96, s14, 7
	v_or_b32_e32 v202, s96, v188
	v_readlane_b32 s56, v242, 1
	v_ashrrev_i32_e32 v203, 31, v202
	v_readlane_b32 s58, v242, 3
	v_readlane_b32 s59, v242, 4
	v_readlane_b32 s62, v242, 7
	v_readlane_b32 s63, v242, 8
	v_lshlrev_b64 v[112:113], 2, v[202:203]
	s_mov_b64 s[58:59], s[62:63]
	v_readlane_b32 s60, v242, 5
	v_readlane_b32 s61, v242, 6
	v_readlane_b32 s64, v242, 9
	v_readlane_b32 s65, v242, 10
	v_lshl_add_u64 v[204:205], s[58:59], 0, v[112:113]
	v_lshl_add_u64 v[118:119], s[52:53], 0, v[112:113]
	s_mov_b64 s[60:61], s[64:65]
	global_load_dwordx4 v[138:141], v[204:205], off
	v_lshl_add_u64 v[120:121], s[4:5], 0, v[112:113]
	global_load_dwordx4 v[142:145], v[118:119], off
	global_load_dwordx4 v[130:133], v[120:121], off
	v_lshl_add_u64 v[118:119], s[76:77], 0, v[112:113]
	v_lshl_add_u64 v[120:121], s[78:79], 0, v[112:113]
	global_load_dwordx4 v[126:129], v[118:119], off
	global_load_dwordx4 v[122:125], v[120:121], off
	v_lshl_add_u64 v[118:119], s[80:81], 0, v[112:113]
	v_lshl_add_u64 v[206:207], s[60:61], 0, v[112:113]
	v_lshl_add_u64 v[112:113], s[82:83], 0, v[112:113]
	global_load_dwordx4 v[118:121], v[118:119], off
	v_mov_b32_e32 v162, 0
	global_load_dwordx4 v[146:149], v[206:207], off
	global_load_dwordx4 v[134:137], v[112:113], off
	s_mov_b64 s[0:1], exec
	v_readlane_b32 s16, v242, 40
	v_readlane_b32 s17, v242, 41
	s_and_b64 s[16:17], s[0:1], s[16:17]
	s_mov_b64 exec, s[16:17]
	s_cbranch_execz .LBB0_933
	ds_write_b128 v215, v[158:161]
	ds_write_b128 v215, v[60:63] offset:16
	ds_write_b128 v215, v[108:111] offset:512
	ds_write_b128 v215, v[56:59] offset:528
	ds_write_b128 v216, v[92:95]
	ds_write_b128 v215, v[28:31] offset:4112
	ds_write_b128 v215, v[88:91] offset:4608
	ds_write_b128 v215, v[24:27] offset:4624

; #define PG8_LAS __attribute__((address_space(3)))
;     __device__ __forceinline__ void operator()(const f32x4 (&acc)[2][2][4][2], const Unit& u, int wr, int wc, int fr, int fq) const {
;     ...
;         asm volatile("s_waitcnt lgkmcnt(0)" ::: "memory"); __builtin_amdgcn_s_barrier(); asm volatile("" ::: "memory");
;         typedef unsigned u32x2 __attribute__((ext_vector_type(2)));
;         u32x2 pk0[2][4];
;         const f32x4 z4 = (f32x4){0.f, 0.f, 0.f, 0.f};
; #pragma unroll
;         for (int n = 0; n < 2; ++n) {
;             const int ch = u.pn * 128 + cl0 + 4 * n;
;             const f32x4 w0a = *(const f32x4*)(cw + ch), w1a = *(const f32x4*)(cw + 11264 + ch), w2a = *(const f32x4*)(cw + 2 * 11264 + ch);
;             const f32x4 w0b = *(const f32x4*)(cw + 5632 + ch), w1b = *(const f32x4*)(cw + 11264 + 5632 + ch), w2b = *(const f32x4*)(cw + 2 * 11264 + 5632 + ch);
;             const f32x4 ba = *(const f32x4*)(cb + ch), bb = *(const f32x4*)(cb + 5632 + ch);
; #pragma unroll
;             for (int ai = 0; ai < 2; ++ai) {
;                 const int q = 2 * ai + wr;
;                 f32x4 haf = z4, hbf = z4, hal = z4, hbl = z4;
;                 if (q > 0) { haf = *(const PG8_LAS f32x4*)(EX + ((q - 1) * 2 + 1) * 256 + cl0 + 4 * n); hbf = *(const PG8_LAS f32x4*)(EX + ((q - 1) * 2 + 1) * 256 + 128 + cl0 + 4 * n); }
;                 if (q < 3) { hal = *(const PG8_LAS f32x4*)(EX + ((q + 1) * 2) * 256 + cl0 + 4 * n); hbl = *(const PG8_LAS f32x4*)(EX + ((q + 1) * 2) * 256 + 128 + cl0 + 4 * n); }
.LBB0_935:
	s_or_b64 exec, exec, s[0:1]
	s_waitcnt lgkmcnt(0)
	s_barrier
	v_cndmask_b32_e64 v112, 0, 1, s[42:43]
	v_cmp_ne_u32_e64 s[18:19], 1, v112
	s_andn2_b64 vcc, exec, s[42:43]
	v_mov_b32_e32 v170, 0
	v_mov_b32_e32 v171, 0
	v_mov_b32_e32 v172, 0
	v_mov_b32_e32 v173, 0
	v_mov_b32_e32 v174, 0
	v_mov_b32_e32 v175, 0
	v_mov_b32_e32 v176, 0
	v_mov_b32_e32 v177, 0
	s_mov_b32 s22, s48
	v_readlane_b32 s57, v242, 2
	v_readlane_b32 s66, v242, 11
	v_readlane_b32 s67, v242, 12
	v_readlane_b32 s68, v242, 13
	v_readlane_b32 s69, v242, 14
	v_readlane_b32 s70, v242, 15
	v_readlane_b32 s71, v242, 16
	s_cbranch_vccnz .LBB0_937
	ds_read_b128 v[174:177], v218
	ds_read_b128 v[170:173], v217
